# v098 + attention: on a unit's last key tile each wave touches the next unit's Q block (and first K/V tile) lines with a 4-byte LDS-DMA into the idle buffer, so the next prologue's DMA hits L2
# speedup vs baseline: 1.0062x; 1.0012x over previous
; #define ATT_STAGE(t, buf) do { _Pragma("unroll") for (int i_ = 0; i_ < 2; ++i_) { \
;         glds16(Kt + (size_t)(t) * 131072, ksrc[i_], (unsigned)__builtin_amdgcn_readfirstlane(ldsb + KBUF + (buf) * 16384 + (w * 2 + i_) * 1024)); \
;         glds16(Vt + (size_t)(t) * 131072, vsrc[i_], (unsigned)__builtin_amdgcn_readfirstlane(ldsb + VBUF + (buf) * 16384 + (w * 2 + i_) * 1024)); } } while (0)
; __device__ __forceinline__ void attn_unit(ATT_LAS unsigned char* lds, const bf16_t* Qg, const bf16_t* Kg, const bf16_t* Vg, bf16_t* Og, int b, int head, int qb, float lam, const float* subg) {
;     ...
;     const size_t rowbase = (size_t)b * SEQ; const int q0 = qb * 256, NT = (q0 + 256) >> 6;
;     const int wq = (w < 4) ? w : 11 - w;
;     const char* Kt = (const char*)(Kg + rowbase * PITCH + head * 128);
;     const char* Vt = (const char*)(Vg + rowbase * PITCH + head * 128);
;     unsigned ksrc[2], vsrc[2];
; #pragma unroll
;     for (int i = 0; i < 2; ++i) { const int ii = w * 2 + i;
;         { const int row = 4 * ii + (lane >> 4), pc = lane & 15; ksrc[i] = (unsigned)(row * 2048 + ((pc ^ (row & 15)) << 4)); }
;         { const int row = 8 * (ii >> 1) + ((lane >> 2) & 7), ch = 4 * (2 * (ii & 1) + (lane >> 5)) + ((lane & 3) ^ ((row >> 2) & 3)); vsrc[i] = (unsigned)(row * 2048 + ch * 16); } }
;     const unsigned ldsb = (unsigned)(uintptr_t)lds;
;     ...
;     ATT_STAGE(0, 0);
;     { const char* Qw = (const char*)(Qg + (rowbase + q0 + wq * 32) * PITCH + head * 128);
; #pragma unroll
;       for (int i = 0; i < 8; ++i) { const int row = 4 * i + (lane >> 4), pc = lane & 15;
;           glds16(Qw, (unsigned)(row * 2048 + ((pc ^ (row & 15)) << 4)), (unsigned)__builtin_amdgcn_readfirstlane(ldsb + QBUF + w * 8192 + i * 1024)); } }
; __global__ void __launch_bounds__(NWAVES * 64, 2) hybrid_fwd(Args a) {
;     ...
;         for (int pu = vcu; pu < BATCH * NH * 8; pu += G) {
;             const int bh = pu >> 3, s = pu & 7, b = bh >> 3, head = bh & 7;
;             for (int k = 0; k < 2; ++k) att::attn_unit(lds, Qb, Kb, Vb, Ab, b, head, k ? s : 15 - s, lam, a.subln_g);
.Lq_prefetch:
	s_cmp_eq_u64 s[88:89], 0
	s_cbranch_scc0 .Lqp_cross
	s_or_b32 s5, s68, s0
	s_mov_b32 s8, s42
	s_mov_b64 vcc, s[64:65]
	s_bitcmp1_b32 s77, 13
	s_cselect_b32 vcc_lo, s66, vcc_lo
	s_cselect_b32 vcc_hi, s67, vcc_hi
	s_branch .Lqp_go
.Lqp_cross:
	s_add_i32 s5, s59, s33
	s_cmpk_gt_i32 s5, 0x3ff
	s_cbranch_scc1 .LBB0_291
	s_lshl_b32 s8, s5, 4
	s_and_b32 s8, s8, 0x380
	s_lshl_b32 s8, s8, 1
	s_lshl_b32 s6, s5, 8
	s_and_b32 s6, s6, 0x700
	s_xor_b32 s6, s6, 0xf00
	s_ashr_i32 s5, s5, 6
	s_lshl_b32 s7, s5, 23
	s_add_u32 s7, s7, s8
	s_lshl_b32 s5, s5, 12
	s_or_b32 s5, s5, s6
	s_bitcmp1_b32 s77, 13
	s_cselect_b32 vcc_lo, s82, s60
	s_cselect_b32 vcc_hi, s83, s61
	s_add_u32 vcc_lo, vcc_lo, s7
	s_addc_u32 vcc_hi, vcc_hi, 0
.Lqp_go:
	s_lshl_b32 s5, s5, 11
	s_add_u32 s6, s48, s5
	s_addc_u32 s7, s49, 0
	s_add_u32 s6, s6, s8
	s_addc_u32 s7, s7, 0
	v_and_b32_e32 v2, 1, v190
	v_lshlrev_b32_e32 v2, 7, v2
	v_and_b32_e32 v3, -2, v190
	v_lshl_or_b32 v3, v3, 10, v2
	s_and_b32 s5, s79, 1
	s_lshl_b32 s5, s5, 14
	s_add_i32 m0, s5, s77
	s_nop 0
	global_load_lds_dword v3, s[6:7]
	s_bitcmp1_b32 s77, 12
	s_cbranch_scc1 .LBB0_291
	v_and_b32_e32 v3, 0x7e, v190
	v_lshl_or_b32 v3, v3, 10, v2
	s_add_i32 m0, m0, 0x100
	s_nop 0
	global_load_lds_dword v3, vcc
	s_branch .LBB0_291
